# phase-2 queue: K/V-sharing groups shrink towards the end of the queue (16/8/4/4 q-blocks per group) to keep the tail balanced
# speedup vs baseline: 1.0259x; 1.0211x over previous
; DI void phase2(const Params& p, char* smem, const int g_wave) {
;     ...
;       if (prm) { int a = it - N0; qb = 31 - (a >> 6); bh = a & 63; } else { qb = 0; bh = it - N2; }
;       const int b = bh >> 3, h = bh & 7;
;       const size_t rowq = prm ? (size_t)b * 8192 + qb * 256 : (size_t)TP + b * 64;
;       u16* qbase = (u16*)(p.ws + WS_Q) + rowq * 1024 + h * 128;
;       const u16* gabase = (const u16*)(p.out + O_Y) + rowq * 1024 + h * 128;
;       const u16* kbase = prm ? (const u16*)(p.ws + WS_K) + (size_t)b * 8192 * 1024 + h * 128 : (const u16*)(p.ws + WS_KC) + (size_t)b * 1088 * 1024 + h * 128;
;       const u16* vtbase = prm ? (const u16*)(p.ws + WS_VT) + (size_t)bh * 128 * 8192 : (const u16*)(p.ws + WS_VTS) + (size_t)bh * 128 * 1088;
;       const int tkv = prm ? 8192 : 1088, nkt = prm ? 4 * (qb + 1) : 17;
.LBB0_692:
	s_add_i32 s4, s6, 0xffffff80
	s_cmp_lt_u32 s4, 0x400
	s_cbranch_scc1 .Lq_A
	s_cmp_lt_u32 s4, 0x600
	s_cbranch_scc1 .Lq_B
	s_cmp_lt_u32 s4, 0x700
	s_cbranch_scc1 .Lq_C
	s_add_i32 s5, s4, 0xfffff900
	s_and_b32 s50, s5, 3
	s_sub_i32 s78, 3, s50
	s_lshr_b32 s50, s5, 2
	s_branch .Lq_done
.Lq_C:
	s_add_i32 s5, s4, 0xfffffa00
	s_and_b32 s50, s5, 3
	s_sub_i32 s78, 7, s50
	s_lshr_b32 s50, s5, 2
	s_branch .Lq_done
.Lq_B:
	s_add_i32 s5, s4, 0xfffffc00
	s_and_b32 s50, s5, 7
	s_sub_i32 s78, 15, s50
	s_lshr_b32 s50, s5, 3
	s_branch .Lq_done
.Lq_A:
	s_and_b32 s50, s4, 15
	s_sub_i32 s78, 31, s50
	s_lshr_b32 s50, s4, 4
.Lq_done:
.LBB0_693:
	s_ashr_i32 s4, s50, 3
	s_mov_b64 s[34:35], -1
	s_and_b64 vcc, exec, s[0:1]
	s_cbranch_vccz .LBB0_697
	s_lshl_b32 s5, s4, 6
	s_ashr_i32 s34, s5, 31
	s_add_u32 s42, s5, 0x10000
	s_addc_u32 s43, s34, 0
	s_ashr_i32 s5, s4, 31
	s_cbranch_execz .LBB0_698
